# attention key loop: the first QK chain (8 MFMAs) also issued in the loop header, in front of the V-tile DMA issue
# speedup vs baseline: 1.0229x; 1.0021x over previous
; #define MFMA16(a, b, c) __builtin_amdgcn_mfma_f32_16x16x32_bf16((a), (b), (c), 0, 0, 0)
; DI int kswz(int key) { return (((key >> 3) & 3) << 2) | (key & 3); }
; DI void attn_item(const Params& p, int l, bool isS, int b, int h, int cp, char* smem) {
;     ...
;   auto issue_v = [&](int kt) {
; #pragma unroll
;     for (int i = 0; i < 2; ++i)
;       __builtin_amdgcn_global_load_lds((const unsigned*)(Vg + (size_t)(vvd + i * 64) * vstride + kt * 64 + vgch * 8), (unsigned*)(Vs + (kt & 1) * 16384 + soff + i * 8192), 16, 0, 0);
;   };
;   auto qk_tile = [&](int kt, f32x4 (&st)[2][4]) {
;     const char* Kb = Ks + (kt & 1) * 16384;
;     bf16x8 kf[2][4][2];
; #pragma unroll
;     for (int mp = 0; mp < 2; ++mp)
; #pragma unroll
;       for (int mt = 0; mt < 4; ++mt) {
;         const int key = 32 * (mt >> 1) + 8 * (fr >> 2) + 4 * (mt & 1) + (fr & 3);
; #pragma unroll
;         for (int ks = 0; ks < 2; ++ks) kf[mp][mt][ks] = *(const bf16x8*)(Kb + key * 256 + (((mp * 8 + ks * 4 + fq) ^ kswz(key)) << 4));
;       }
; #pragma unroll
;     for (int mp = 0; mp < 2; ++mp)
; #pragma unroll
;       for (int mt = 0; mt < 4; ++mt) {
;         f32x4 a = MFMA16(kf[mp][mt][0], qf[mp][0], (f32x4{0.f, 0.f, 0.f, 0.f}));
;         st[mp][mt] = MFMA16(kf[mp][mt][1], qf[mp][1], a);
;       }
.LBB0_1370:
	s_add_i32 s20, s34, 0x4000
	s_and_b32 s20, s20, 0x4000
	v_add_u32_e32 v248, s20, v151
	v_add_u32_e32 v170, v248, v146
	v_add_u32_e32 v171, v248, v147
	v_add_u32_e32 v242, v248, v148
	v_add_u32_e32 v243, v248, v149
	s_and_b32 s24, s34, 0x4000
	v_add_u32_e32 v249, s24, v150
	v_add_u32_e32 v244, v249, v137
	v_add_u32_e32 v245, v249, v145
	ds_read_b128 v[154:157], v170
	ds_read_b128 v[158:161], v171
	ds_read_b128 v[162:165], v170 offset:1024
	ds_read_b128 v[166:169], v171 offset:1024
	ds_read_b128 v[176:179], v170 offset:8192
	ds_read_b128 v[180:183], v171 offset:8192
	ds_read_b128 v[198:201], v170 offset:9216
	ds_read_b128 v[202:205], v171 offset:9216
	ds_read_b128 v[206:209], v242
	ds_read_b128 v[214:217], v243
	ds_read_b128 v[218:221], v242 offset:1024
	ds_read_b128 v[222:225], v243 offset:1024
	ds_read_b128 v[226:229], v242 offset:8192
	ds_read_b128 v[230:233], v243 offset:8192
	ds_read_b128 v[234:237], v242 offset:9216
	s_waitcnt lgkmcnt(13)
	v_mfma_f32_16x16x32_bf16 v[124:127], v[154:157], v[8:11], 0
	v_mfma_f32_16x16x32_bf16 v[124:127], v[158:161], v[4:7], v[124:127]
	ds_read_b128 v[238:241], v243 offset:9216
	s_waitcnt lgkmcnt(12)
	v_mfma_f32_16x16x32_bf16 v[120:123], v[162:165], v[8:11], 0
	v_mfma_f32_16x16x32_bf16 v[120:123], v[166:169], v[4:7], v[120:123]
	s_waitcnt lgkmcnt(10)
	v_mfma_f32_16x16x32_bf16 v[112:115], v[176:179], v[8:11], 0
	v_mfma_f32_16x16x32_bf16 v[112:115], v[180:183], v[4:7], v[112:115]
	s_waitcnt lgkmcnt(8)
	v_mfma_f32_16x16x32_bf16 v[116:119], v[198:201], v[8:11], 0
	v_mfma_f32_16x16x32_bf16 v[116:119], v[202:205], v[4:7], v[116:119]
	s_add_i32 s35, s30, 1
	s_cmp_ge_i32 s35, s9
	s_cbranch_scc1 .LBB0_1372
	s_add_i32 s20, s34, 0x4000
	s_and_b32 s20, s20, 0x4000
	v_add_u32_e32 v100, s20, v133
	v_add_u32_e32 v104, 0x8000, v100
	s_add_i32 s20, s11, 64
	v_add_u32_e32 v105, 0xa000, v100
	s_lshl_b64 s[28:29], s[20:21], 1
	v_readfirstlane_b32 s20, v104
	v_lshl_add_u64 v[102:103], v[138:139], 0, s[28:29]
	s_mov_b32 m0, s20
	v_readfirstlane_b32 s20, v105
	v_lshl_add_u64 v[100:101], v[140:141], 0, s[28:29]
	global_load_lds_dwordx4 v[102:103], off
	s_mov_b32 m0, s20
	s_nop 0
	global_load_lds_dwordx4 v[100:101], off

; #define MFMA16(a, b, c) __builtin_amdgcn_mfma_f32_16x16x32_bf16((a), (b), (c), 0, 0, 0)
; DI void attn_item(const Params& p, int l, bool isS, int b, int h, int cp, char* smem) {
;     ...
; #pragma unroll
;     for (int mp = 0; mp < 2; ++mp)
; #pragma unroll
;       for (int mt = 0; mt < 4; ++mt) {
;         f32x4 a = MFMA16(kf[mp][mt][0], qf[mp][0], (f32x4{0.f, 0.f, 0.f, 0.f}));
;         st[mp][mt] = MFMA16(kf[mp][mt][1], qf[mp][1], a);
;       }
;     if ((kt + 1) * 64 > klen) {
;       asm volatile("" ::: "memory");
; #pragma unroll
;       for (int mp = 0; mp < 2; ++mp)
; #pragma unroll
;         for (int mt = 0; mt < 4; ++mt)
; #pragma unroll
;           for (int j = 0; j < 4; ++j) {
;             const int key = kt * 64 + 32 * (mt >> 1) + 8 * fq + 4 * (mt & 1) + j;
;             if (key >= klen) st[mp][mt][j] = -INFINITY;
;           }
;     }
;     ...
;       const char* Vb = Vs + (j & 1) * 16384;
; #pragma unroll
;       for (int nh = 0; nh < 2; ++nh) {
;         bf16x8 vf[4][2];
; #pragma unroll
;         for (int n = 0; n < 4; ++n) {
;           const int vd = (nh * 4 + n) * 16 + fr;
; #pragma unroll
;           for (int s = 0; s < 2; ++s) vf[n][s] = *(const bf16x8*)(Vb + vd * 128 + (((s * 4 + fq) ^ ((vd >> 1) & 7)) << 4));
.LBB0_1376:
	s_andn2_saveexec_b64 s[28:29], s[28:29]
	s_cbranch_execz .LBB0_1386
	ds_read_b128 v[154:157], v244 offset:32768
	ds_read_b128 v[158:161], v245 offset:32768
	ds_read_b128 v[162:165], v244 offset:34816
	ds_read_b128 v[166:169], v245 offset:34816
	ds_read_b128 v[176:179], v244 offset:36864
	ds_read_b128 v[180:183], v245 offset:36864
	ds_read_b128 v[198:201], v244 offset:38912
	s_waitcnt lgkmcnt(13)
	v_mfma_f32_16x16x32_bf16 v[104:107], v[206:209], v[16:19], 0
	v_mfma_f32_16x16x32_bf16 v[104:107], v[214:217], v[12:15], v[104:107]
	ds_read_b128 v[202:205], v245 offset:38912
	s_waitcnt lgkmcnt(12)
	v_mfma_f32_16x16x32_bf16 v[108:111], v[218:221], v[16:19], 0
	v_mfma_f32_16x16x32_bf16 v[108:111], v[222:225], v[12:15], v[108:111]
	s_waitcnt lgkmcnt(10)
	v_mfma_f32_16x16x32_bf16 v[100:103], v[226:229], v[16:19], 0
	v_mfma_f32_16x16x32_bf16 v[100:103], v[230:233], v[12:15], v[100:103]
	s_waitcnt lgkmcnt(8)
	v_mfma_f32_16x16x32_bf16 v[128:131], v[234:237], v[16:19], 0
	v_mfma_f32_16x16x32_bf16 v[128:131], v[238:241], v[12:15], v[128:131]
	ds_read_b128 v[206:209], v244 offset:40960
	ds_read_b128 v[214:217], v245 offset:40960
	ds_read_b128 v[218:221], v244 offset:43008
	ds_read_b128 v[222:225], v245 offset:43008
	ds_read_b128 v[226:229], v244 offset:45056
	ds_read_b128 v[230:233], v245 offset:45056
	ds_read_b128 v[234:237], v244 offset:47104
	s_add_i32 s20, s11, 0x80
	s_cmp_le_i32 s20, s10
	s_cbranch_scc1 .Lat_nomask
	s_nop 7
	v_add_u32_e32 v246, s11, v132
	v_add_u32_e32 v247, 64, v246
	v_cmp_gt_i32_e64 s[38:39], s10, v247
	v_add_u32_e32 v247, 0x41, v246
	v_cmp_gt_i32_e64 s[40:41], s10, v247
	v_add_u32_e32 v247, 0x42, v246
	v_cmp_gt_i32_e64 s[42:43], s10, v247
	v_add_u32_e32 v247, 0x43, v246
	v_cmp_gt_i32_e64 s[44:45], s10, v247
	v_add_u32_e32 v247, 0x44, v246
	v_cmp_gt_i32_e64 s[46:47], s10, v247
	v_add_u32_e32 v247, 0x45, v246
	v_cmp_gt_i32_e64 s[48:49], s10, v247
	v_add_u32_e32 v247, 0x46, v246
	v_cmp_gt_i32_e64 s[50:51], s10, v247
	v_add_u32_e32 v247, 0x47, v246
	v_cmp_gt_i32_e64 s[52:53], s10, v247
	v_add_u32_e32 v247, 0x60, v246
	v_cmp_gt_i32_e64 s[54:55], s10, v247
	v_add_u32_e32 v247, 0x61, v246
	v_cmp_gt_i32_e64 s[56:57], s10, v247
	v_add_u32_e32 v247, 0x62, v246
	v_cmp_gt_i32_e64 s[58:59], s10, v247
	v_add_u32_e32 v247, 0x63, v246
	v_cmp_gt_i32_e64 s[60:61], s10, v247
	v_add_u32_e32 v247, 0x64, v246
	v_cmp_gt_i32_e64 s[62:63], s10, v247
	v_add_u32_e32 v247, 0x65, v246
	v_cmp_gt_i32_e64 s[64:65], s10, v247
	v_add_u32_e32 v247, 0x66, v246
	v_add_u32_e32 v246, 0x67, v246
	v_cmp_gt_i32_e64 s[66:67], s10, v246
	v_cmp_gt_i32_e64 s[68:69], s10, v247
	v_cmp_le_i32_e32 vcc, s10, v246
	v_cndmask_b32_e64 v119, v3, v119, s[66:67]
	s_or_b64 s[66:67], s[66:67], s[68:69]
	v_cndmask_b32_e64 v118, v3, v118, s[66:67]
	s_or_b64 s[66:67], s[66:67], s[64:65]
	s_or_b64 s[64:65], s[68:69], s[64:65]
	v_cndmask_b32_e64 v117, v3, v117, s[66:67]
	s_or_b64 s[66:67], s[66:67], s[62:63]
	s_or_b64 s[62:63], s[64:65], s[62:63]
	v_cndmask_b32_e64 v116, v3, v116, s[66:67]
	s_or_b64 s[66:67], s[66:67], s[60:61]
	s_or_b64 s[60:61], s[62:63], s[60:61]
	v_cndmask_b32_e64 v115, v3, v115, s[66:67]
	s_or_b64 s[66:67], s[66:67], s[58:59]
	s_or_b64 s[58:59], s[60:61], s[58:59]
	v_cndmask_b32_e64 v114, v3, v114, s[66:67]
	s_or_b64 s[66:67], s[66:67], s[56:57]
	s_or_b64 s[56:57], s[58:59], s[56:57]
	v_cndmask_b32_e64 v113, v3, v113, s[66:67]
	s_or_b64 s[66:67], s[66:67], s[54:55]
	s_or_b64 s[54:55], s[56:57], s[54:55]
	v_cndmask_b32_e64 v112, v3, v112, s[66:67]
	s_or_b64 s[66:67], s[66:67], s[52:53]
	s_or_b64 s[52:53], s[54:55], s[52:53]
	v_cndmask_b32_e64 v123, v3, v123, s[66:67]
	s_or_b64 s[66:67], s[66:67], s[50:51]
	s_or_b64 s[50:51], s[52:53], s[50:51]
	v_cndmask_b32_e64 v122, v3, v122, s[66:67]
	s_or_b64 s[66:67], s[66:67], s[48:49]
	s_or_b64 s[48:49], s[50:51], s[48:49]
	v_cndmask_b32_e64 v121, v3, v121, s[66:67]
	s_or_b64 s[66:67], s[66:67], s[46:47]
	s_or_b64 s[46:47], s[48:49], s[46:47]
	v_cndmask_b32_e64 v120, v3, v120, s[66:67]
	s_or_b64 s[66:67], s[66:67], s[44:45]
	s_or_b64 s[44:45], s[46:47], s[44:45]
	v_cndmask_b32_e64 v127, v3, v127, s[66:67]
	s_or_b64 s[66:67], s[66:67], s[42:43]
	s_or_b64 s[42:43], s[44:45], s[42:43]
	v_cndmask_b32_e64 v126, v3, v126, s[66:67]
	s_or_b64 s[66:67], s[66:67], s[40:41]
	s_or_b64 s[40:41], s[42:43], s[40:41]
	v_cndmask_b32_e64 v125, v3, v125, s[66:67]
	s_or_b64 s[66:67], s[66:67], s[38:39]
	s_or_b64 s[38:39], s[40:41], s[38:39]
	v_cndmask_b32_e64 v130, v3, v130, s[68:69]
	v_cndmask_b32_e64 v124, v3, v124, s[66:67]
	v_cndmask_b32_e64 v129, v3, v129, s[64:65]
	v_cndmask_b32_e64 v128, v3, v128, s[62:63]
	v_cndmask_b32_e64 v103, v3, v103, s[60:61]
	v_cndmask_b32_e64 v102, v3, v102, s[58:59]
	v_cndmask_b32_e64 v101, v3, v101, s[56:57]
	v_cndmask_b32_e64 v100, v3, v100, s[54:55]
	v_cndmask_b32_e64 v111, v3, v111, s[52:53]
	v_cndmask_b32_e64 v110, v3, v110, s[50:51]
	v_cndmask_b32_e64 v109, v3, v109, s[48:49]
	v_cndmask_b32_e64 v108, v3, v108, s[46:47]
	v_cndmask_b32_e64 v107, v3, v107, s[44:45]
	v_cndmask_b32_e64 v106, v3, v106, s[42:43]
	v_cndmask_b32_e64 v105, v3, v105, s[40:41]
	v_cndmask_b32_e64 v104, v3, v104, s[38:39]
	s_and_saveexec_b64 s[30:31], vcc
	v_mov_b32_e32 v131, 0xff800000
	s_or_b64 exec, exec, s[30:31]
